# strategy 7 (instruction selection): phase-3 f32->bf16 RNE via v_cvt_pk_bf16_f32 + ds_write_b16 instead of the bfe/add3 bit trick + d16_hi write (151 sites, same rounding)
# speedup vs baseline: 1.0044x; 1.0032x over previous
.LBB0_355:
	s_and_b64 vcc, exec, s[18:19]
	s_cbranch_vccz .LBB0_421
	v_add_u32_e32 v2, v171, v187
	ds_read_b128 v[4:7], v2 offset:272
	v_mov_b32_e32 v2, v188
	s_waitcnt lgkmcnt(0)
	v_fma_f32 v17, -v195, v4, v196
	v_add_u32_e32 v3, 0, v2
	ds_read_b128 v[6:9], v3 offset:544
	s_nop 0
	v_add_u32_e32 v3, 0, v2
	s_waitcnt lgkmcnt(0)
	ds_read_b128 v[8:11], v3 offset:816
	v_fma_f32 v3, -v195, v6, v197
	v_fma_f32 v4, -v7, v17, 0
	v_add_f32_e32 v15, v4, v3
	s_nop 0
	v_add_u32_e32 v3, 0, v2
	ds_read_b128 v[4:7], v3 offset:1088
	s_waitcnt lgkmcnt(1)
	v_fma_f32 v3, -v195, v8, v198
	v_fma_f32 v8, -v17, v9, 0
	v_fma_f32 v9, -v10, v15, 0
	v_add_f32_e32 v3, v8, v3
	v_add_f32_e32 v13, v9, v3
	s_nop 0
	v_add_u32_e32 v3, 0, v2
	ds_read_b128 v[18:21], v3 offset:1360
	ds_read_b128 v[8:11], v3 offset:1376
	s_waitcnt lgkmcnt(2)
	v_fma_f32 v3, -v195, v4, v199
	v_fma_f32 v4, -v17, v5, 0
	v_fma_f32 v5, -v15, v6, 0
	v_fma_f32 v6, -v7, v13, 0
	v_add_f32_e32 v3, v4, v3
	v_add_f32_e32 v4, v6, v5
	s_waitcnt lgkmcnt(0)
	v_add_f32_e32 v11, v4, v3
	v_fma_f32 v9, -v17, v19, 0
	v_add_u32_e32 v3, 0, v2
	ds_read_b128 v[4:7], v3 offset:1632
	ds_read_b128 v[22:25], v3 offset:1648
	v_fma_f32 v3, -v195, v18, v200
	v_fma_f32 v10, -v15, v20, 0
	v_fma_f32 v12, -v13, v21, 0
	v_fma_f32 v3, -v8, v11, v3
	v_add_f32_e32 v3, v9, v3
	v_add_f32_e32 v8, v12, v10
	v_add_f32_e32 v9, v8, v3
	s_nop 0
	v_add_u32_e32 v3, 0, v2
	ds_read_b128 v[18:21], v3 offset:1904
	ds_read_b128 v[28:31], v3 offset:1920
	s_waitcnt lgkmcnt(3)
	v_fma_f32 v3, -v195, v4, v201
	v_fma_f32 v4, -v17, v5, 0
	v_fma_f32 v5, -v15, v6, 0
	v_fma_f32 v6, -v13, v7, 0
	s_waitcnt lgkmcnt(2)
	v_fma_f32 v3, -v11, v22, v3
	v_fma_f32 v4, -v23, v9, v4
	v_add_f32_e32 v3, v4, v3
	v_add_f32_e32 v4, v6, v5
	v_add_f32_e32 v7, v4, v3
	s_waitcnt lgkmcnt(1)
	v_fma_f32 v4, -v17, v19, 0
	v_add_u32_e32 v3, 0, v2
	ds_read_b128 v[22:25], v3 offset:2176
	ds_read_b128 v[32:35], v3 offset:2192
	v_fma_f32 v3, -v195, v18, v202
	v_fma_f32 v5, -v15, v20, 0
	v_fma_f32 v6, -v13, v21, 0
	s_waitcnt lgkmcnt(2)
	v_fma_f32 v3, -v11, v28, v3
	v_fma_f32 v4, -v9, v29, v4
	v_fma_f32 v5, -v30, v7, v5
	v_add_f32_e32 v3, v4, v3
	v_add_f32_e32 v4, v6, v5
	v_add_f32_e32 v4, v4, v3
	s_waitcnt lgkmcnt(1)
	v_fma_f32 v5, -v17, v23, 0
	v_add_u32_e32 v3, 0, v2
	ds_read_b128 v[18:21], v3 offset:2448
	ds_read_b128 v[28:31], v3 offset:2464
	ds_read_b128 v[36:39], v3 offset:2480
	v_fma_f32 v3, -v195, v22, v203
	v_fma_f32 v6, -v15, v24, 0
	v_fma_f32 v8, -v13, v25, 0
	s_waitcnt lgkmcnt(3)
	v_fma_f32 v3, -v11, v32, v3
	v_fma_f32 v5, -v9, v33, v5
	v_fma_f32 v6, -v7, v34, v6
	v_fma_f32 v8, -v35, v4, v8
	v_add_f32_e32 v3, v5, v3
	v_add_f32_e32 v5, v8, v6
	v_add_f32_e32 v5, v5, v3
	s_waitcnt lgkmcnt(2)
	v_fma_f32 v6, -v17, v19, 0
	v_add_u32_e32 v3, 0, v2
	ds_read_b128 v[22:25], v3 offset:2720
	ds_read_b128 v[32:35], v3 offset:2736
	s_waitcnt lgkmcnt(2)
	ds_read_b128 v[38:41], v3 offset:2752
	v_fma_f32 v3, -v195, v18, v204
	v_fma_f32 v8, -v15, v20, 0
	v_fma_f32 v10, -v13, v21, 0
	v_fma_f32 v3, -v11, v28, v3
	v_fma_f32 v6, -v9, v29, v6
	v_fma_f32 v8, -v7, v30, v8
	v_fma_f32 v10, -v4, v31, v10
	v_fma_f32 v3, -v36, v5, v3
	v_add_f32_e32 v3, v6, v3
	v_add_f32_e32 v6, v10, v8
	v_add_f32_e32 v6, v6, v3
	s_waitcnt lgkmcnt(2)
	v_fma_f32 v8, -v17, v23, 0
	v_add_u32_e32 v3, 0, v2
	ds_read_b128 v[18:21], v3 offset:2992
	ds_read_b128 v[28:31], v3 offset:3008
	s_waitcnt lgkmcnt(2)
	ds_read_b128 v[40:43], v3 offset:3024
	v_fma_f32 v3, -v195, v22, v205
	v_fma_f32 v10, -v15, v24, 0
	v_fma_f32 v12, -v13, v25, 0
	v_fma_f32 v3, -v11, v32, v3
	v_fma_f32 v8, -v9, v33, v8
	v_fma_f32 v10, -v7, v34, v10
	v_fma_f32 v12, -v4, v35, v12
	v_fma_f32 v3, -v5, v38, v3
	v_fma_f32 v8, -v39, v6, v8
	v_add_f32_e32 v3, v8, v3
	v_add_f32_e32 v8, v12, v10
	v_add_f32_e32 v8, v8, v3
	s_waitcnt lgkmcnt(2)
	v_fma_f32 v10, -v17, v19, 0
	v_add_u32_e32 v3, 0, v2
	ds_read_b128 v[22:25], v3 offset:3264
	ds_read_b128 v[32:35], v3 offset:3280
	ds_read_b128 v[36:39], v3 offset:3296
	v_fma_f32 v3, -v195, v18, v206
	v_fma_f32 v12, -v15, v20, 0
	v_fma_f32 v14, -v13, v21, 0
	s_waitcnt lgkmcnt(4)
	v_fma_f32 v3, -v11, v28, v3
	v_fma_f32 v10, -v9, v29, v10
	v_fma_f32 v12, -v7, v30, v12
	v_fma_f32 v14, -v4, v31, v14
	s_waitcnt lgkmcnt(3)
	v_fma_f32 v3, -v5, v40, v3
	v_fma_f32 v10, -v6, v41, v10
	v_fma_f32 v12, -v42, v8, v12
	v_add_f32_e32 v3, v10, v3
	v_add_f32_e32 v10, v14, v12
	v_add_f32_e32 v10, v10, v3
	s_waitcnt lgkmcnt(2)
	v_fma_f32 v12, -v17, v23, 0
	v_add_u32_e32 v3, 0, v2
	ds_read_b128 v[18:21], v3 offset:3536
	ds_read_b128 v[28:31], v3 offset:3552
	ds_read_b128 v[40:43], v3 offset:3568
	ds_read_b128 v[44:47], v3 offset:3584
	v_fma_f32 v3, -v195, v22, v207
	v_fma_f32 v14, -v15, v24, 0
	v_fma_f32 v16, -v13, v25, 0
	s_waitcnt lgkmcnt(5)
	v_fma_f32 v3, -v11, v32, v3
	v_fma_f32 v12, -v9, v33, v12
	v_fma_f32 v14, -v7, v34, v14
	v_fma_f32 v16, -v4, v35, v16
	s_waitcnt lgkmcnt(4)
	v_fma_f32 v3, -v5, v36, v3
	v_fma_f32 v12, -v6, v37, v12
	v_fma_f32 v14, -v8, v38, v14
	v_fma_f32 v16, -v39, v10, v16
	v_add_f32_e32 v3, v12, v3
	v_add_f32_e32 v12, v16, v14
	v_add_f32_e32 v12, v12, v3
	s_waitcnt lgkmcnt(3)
	v_fma_f32 v14, -v17, v19, 0
	v_add_u32_e32 v3, 0, v2
	ds_read_b128 v[22:25], v3 offset:3808
	ds_read_b128 v[32:35], v3 offset:3824
	ds_read_b128 v[36:39], v3 offset:3840
	s_waitcnt lgkmcnt(3)
	ds_read_b128 v[46:49], v3 offset:3856
	v_fma_f32 v3, -v195, v18, v208
	v_fma_f32 v16, -v15, v20, 0
	v_fma_f32 v18, -v13, v21, 0
	v_fma_f32 v3, -v11, v28, v3
	v_fma_f32 v14, -v9, v29, v14
	v_fma_f32 v16, -v7, v30, v16
	v_fma_f32 v18, -v4, v31, v18
	v_fma_f32 v3, -v5, v40, v3
	v_fma_f32 v14, -v6, v41, v14
	v_fma_f32 v16, -v8, v42, v16
	v_fma_f32 v18, -v10, v43, v18
	v_fma_f32 v3, -v44, v12, v3
	v_add_f32_e32 v3, v14, v3
	v_add_f32_e32 v14, v18, v16
	v_add_f32_e32 v14, v14, v3
	s_waitcnt lgkmcnt(3)
	v_fma_f32 v16, -v17, v23, 0
	v_add_u32_e32 v3, 0, v2
	ds_read_b128 v[18:21], v3 offset:4080
	ds_read_b128 v[28:31], v3 offset:4096
	ds_read_b128 v[40:43], v3 offset:4112
	s_waitcnt lgkmcnt(3)
	ds_read_b128 v[48:51], v3 offset:4128
	v_fma_f32 v3, -v195, v22, v209
	v_fma_f32 v22, -v15, v24, 0
	v_fma_f32 v23, -v13, v25, 0
	v_fma_f32 v3, -v11, v32, v3
	v_fma_f32 v16, -v9, v33, v16
	v_fma_f32 v22, -v7, v34, v22
	v_fma_f32 v23, -v4, v35, v23
	v_fma_f32 v3, -v5, v36, v3
	v_fma_f32 v16, -v6, v37, v16
	v_fma_f32 v22, -v8, v38, v22
	v_fma_f32 v23, -v10, v39, v23
	v_fma_f32 v3, -v12, v46, v3
	v_fma_f32 v16, -v47, v14, v16
	v_add_f32_e32 v3, v16, v3
	v_add_f32_e32 v16, v23, v22
	v_add_f32_e32 v16, v16, v3
	s_nop 0
	v_add_u32_e32 v3, 0, v2
	ds_read_b128 v[22:25], v3 offset:4352
	ds_read_b128 v[32:35], v3 offset:4368
	ds_read_b128 v[36:39], v3 offset:4384
	ds_read_b128 v[44:47], v3 offset:4400
	s_waitcnt lgkmcnt(7)
	v_fma_f32 v3, -v195, v18, v210
	v_fma_f32 v18, -v17, v19, 0
	v_fma_f32 v19, -v15, v20, 0
	v_fma_f32 v20, -v13, v21, 0
	s_waitcnt lgkmcnt(6)
	v_fma_f32 v3, -v11, v28, v3
	v_fma_f32 v18, -v9, v29, v18
	v_fma_f32 v19, -v7, v30, v19
	v_fma_f32 v20, -v4, v31, v20
	s_waitcnt lgkmcnt(5)
	v_fma_f32 v3, -v5, v40, v3
	v_fma_f32 v18, -v6, v41, v18
	v_fma_f32 v19, -v8, v42, v19
	v_fma_f32 v20, -v10, v43, v20
	s_waitcnt lgkmcnt(4)
	v_fma_f32 v3, -v12, v48, v3
	v_fma_f32 v18, -v14, v49, v18
	v_fma_f32 v19, -v50, v16, v19
	v_add_f32_e32 v3, v18, v3
	v_add_f32_e32 v18, v20, v19
	v_add_f32_e32 v18, v18, v3
	s_waitcnt lgkmcnt(3)
	v_fma_f32 v19, -v17, v23, 0
	v_add_u32_e32 v3, 0, v2
	ds_read_b128 v[28:31], v3 offset:4624
	ds_read_b128 v[40:43], v3 offset:4640
	ds_read_b128 v[48:51], v3 offset:4656
	ds_read_b128 v[52:55], v3 offset:4672
	ds_read_b128 v[56:59], v3 offset:4688
	v_fma_f32 v3, -v195, v22, v211
	v_fma_f32 v20, -v15, v24, 0
	v_fma_f32 v21, -v13, v25, 0
	s_waitcnt lgkmcnt(7)
	v_fma_f32 v3, -v11, v32, v3
	v_fma_f32 v19, -v9, v33, v19
	v_fma_f32 v20, -v7, v34, v20
	v_fma_f32 v21, -v4, v35, v21
	s_waitcnt lgkmcnt(6)
	v_fma_f32 v3, -v5, v36, v3
	v_fma_f32 v19, -v6, v37, v19
	v_fma_f32 v20, -v8, v38, v20
	v_fma_f32 v21, -v10, v39, v21
	s_waitcnt lgkmcnt(5)
	v_fma_f32 v3, -v12, v44, v3
	v_fma_f32 v19, -v14, v45, v19
	v_fma_f32 v20, -v16, v46, v20
	v_fma_f32 v21, -v47, v18, v21
	v_add_f32_e32 v3, v19, v3
	v_add_f32_e32 v19, v21, v20
	v_add_f32_e32 v19, v19, v3
	s_waitcnt lgkmcnt(4)
	v_fma_f32 v20, -v17, v29, 0
	v_add_u32_e32 v3, 0, v2
	ds_read_b128 v[22:25], v3 offset:4896
	ds_read_b128 v[32:35], v3 offset:4912
	ds_read_b128 v[36:39], v3 offset:4928
	ds_read_b128 v[44:47], v3 offset:4944
	s_waitcnt lgkmcnt(4)
	ds_read_b128 v[58:61], v3 offset:4960
	v_fma_f32 v3, -v195, v28, v212
	v_fma_f32 v21, -v15, v30, 0
	v_fma_f32 v27, -v13, v31, 0
	v_fma_f32 v3, -v11, v40, v3
	v_fma_f32 v20, -v9, v41, v20
	v_fma_f32 v21, -v7, v42, v21
	v_fma_f32 v27, -v4, v43, v27
	v_fma_f32 v3, -v5, v48, v3
	v_fma_f32 v20, -v6, v49, v20
	v_fma_f32 v21, -v8, v50, v21
	v_fma_f32 v27, -v10, v51, v27
	v_fma_f32 v3, -v12, v52, v3
	v_fma_f32 v20, -v14, v53, v20
	v_fma_f32 v21, -v16, v54, v21
	v_fma_f32 v27, -v18, v55, v27
	v_fma_f32 v3, -v56, v19, v3
	v_add_f32_e32 v3, v20, v3
	v_add_f32_e32 v20, v27, v21
	v_add_f32_e32 v20, v20, v3
	s_waitcnt lgkmcnt(4)
	v_fma_f32 v21, -v17, v23, 0
	v_add_u32_e32 v3, 0, v2
	ds_read_b128 v[28:31], v3 offset:5168
	ds_read_b128 v[40:43], v3 offset:5184
	ds_read_b128 v[48:51], v3 offset:5200
	ds_read_b128 v[52:55], v3 offset:5216
	s_waitcnt lgkmcnt(4)
	ds_read_b128 v[60:63], v3 offset:5232
	v_fma_f32 v3, -v195, v22, v213
	v_fma_f32 v22, -v15, v24, 0
	v_fma_f32 v23, -v13, v25, 0
	v_fma_f32 v3, -v11, v32, v3
	v_fma_f32 v21, -v9, v33, v21
	v_fma_f32 v22, -v7, v34, v22
	v_fma_f32 v23, -v4, v35, v23
	v_fma_f32 v3, -v5, v36, v3
	v_fma_f32 v21, -v6, v37, v21
	v_fma_f32 v22, -v8, v38, v22
	v_fma_f32 v23, -v10, v39, v23
	v_fma_f32 v3, -v12, v44, v3
	v_fma_f32 v21, -v14, v45, v21
	v_fma_f32 v22, -v16, v46, v22
	v_fma_f32 v23, -v18, v47, v23
	v_fma_f32 v3, -v19, v58, v3
	v_fma_f32 v21, -v59, v20, v21
	v_add_f32_e32 v3, v21, v3
	v_add_f32_e32 v21, v23, v22
	v_add_f32_e32 v21, v21, v3
	s_waitcnt lgkmcnt(4)
	v_fma_f32 v22, -v17, v29, 0
	v_add_u32_e32 v3, 0, v2
	ds_read_b128 v[32:35], v3 offset:5440
	ds_read_b128 v[36:39], v3 offset:5456
	ds_read_b128 v[44:47], v3 offset:5472
	ds_read_b128 v[56:59], v3 offset:5488
	ds_read_b128 v[64:67], v3 offset:5504
	v_fma_f32 v3, -v195, v28, v214
	v_fma_f32 v23, -v15, v30, 0
	v_fma_f32 v24, -v13, v31, 0
	s_waitcnt lgkmcnt(8)
	v_fma_f32 v3, -v11, v40, v3
	v_fma_f32 v22, -v9, v41, v22
	v_fma_f32 v23, -v7, v42, v23
	v_fma_f32 v24, -v4, v43, v24
	s_waitcnt lgkmcnt(7)
	v_fma_f32 v3, -v5, v48, v3
	v_fma_f32 v22, -v6, v49, v22
	v_fma_f32 v23, -v8, v50, v23
	v_fma_f32 v24, -v10, v51, v24
	s_waitcnt lgkmcnt(6)
	v_fma_f32 v3, -v12, v52, v3
	v_fma_f32 v22, -v14, v53, v22
	v_fma_f32 v23, -v16, v54, v23
	v_fma_f32 v24, -v18, v55, v24
	s_waitcnt lgkmcnt(5)
	v_fma_f32 v3, -v19, v60, v3
	v_fma_f32 v22, -v20, v61, v22
	v_fma_f32 v23, -v62, v21, v23
	v_add_f32_e32 v3, v22, v3
	v_add_f32_e32 v22, v24, v23
	v_add_f32_e32 v22, v22, v3
	s_waitcnt lgkmcnt(4)
	v_fma_f32 v23, -v17, v33, 0
	v_add_u32_e32 v3, 0, v2
	ds_read_b128 v[28:31], v3 offset:5712
	ds_read_b128 v[40:43], v3 offset:5728
	ds_read_b128 v[48:51], v3 offset:5744
	ds_read_b128 v[52:55], v3 offset:5760
	ds_read_b128 v[60:63], v3 offset:5776
	ds_read_b128 v[68:71], v3 offset:5792
	v_fma_f32 v3, -v195, v32, v215
	v_fma_f32 v24, -v15, v34, 0
	v_fma_f32 v25, -v13, v35, 0
	s_waitcnt lgkmcnt(9)
	v_fma_f32 v3, -v11, v36, v3
	v_fma_f32 v23, -v9, v37, v23
	v_fma_f32 v24, -v7, v38, v24
	v_fma_f32 v25, -v4, v39, v25
	s_waitcnt lgkmcnt(8)
	v_fma_f32 v3, -v5, v44, v3
	v_fma_f32 v23, -v6, v45, v23
	v_fma_f32 v24, -v8, v46, v24
	v_fma_f32 v25, -v10, v47, v25
	s_waitcnt lgkmcnt(7)
	v_fma_f32 v3, -v12, v56, v3
	v_fma_f32 v23, -v14, v57, v23
	v_fma_f32 v24, -v16, v58, v24
	v_fma_f32 v25, -v18, v59, v25
	s_waitcnt lgkmcnt(6)
	v_fma_f32 v3, -v19, v64, v3
	v_fma_f32 v23, -v20, v65, v23
	v_fma_f32 v24, -v21, v66, v24
	v_fma_f32 v25, -v67, v22, v25
	v_add_f32_e32 v3, v23, v3
	v_add_f32_e32 v23, v25, v24
	v_add_f32_e32 v23, v23, v3
	s_waitcnt lgkmcnt(5)
	v_fma_f32 v24, -v17, v29, 0
	v_add_u32_e32 v3, 0, v2
	ds_read_b128 v[32:35], v3 offset:5984
	ds_read_b128 v[36:39], v3 offset:6000
	ds_read_b128 v[44:47], v3 offset:6016
	ds_read_b128 v[56:59], v3 offset:6032
	ds_read_b128 v[64:67], v3 offset:6048
	s_waitcnt lgkmcnt(5)
	ds_read_b128 v[70:73], v3 offset:6064
	v_fma_f32 v3, -v195, v28, v216
	v_fma_f32 v25, -v15, v30, 0
	v_fma_f32 v27, -v13, v31, 0
	v_fma_f32 v3, -v11, v40, v3
	v_fma_f32 v24, -v9, v41, v24
	v_fma_f32 v25, -v7, v42, v25
	v_fma_f32 v27, -v4, v43, v27
	v_fma_f32 v3, -v5, v48, v3
	v_fma_f32 v24, -v6, v49, v24
	v_fma_f32 v25, -v8, v50, v25
	v_fma_f32 v27, -v10, v51, v27
	v_fma_f32 v3, -v12, v52, v3
	v_fma_f32 v24, -v14, v53, v24
	v_fma_f32 v25, -v16, v54, v25
	v_fma_f32 v27, -v18, v55, v27
	v_fma_f32 v3, -v19, v60, v3
	v_fma_f32 v24, -v20, v61, v24
	v_fma_f32 v25, -v21, v62, v25
	v_fma_f32 v27, -v22, v63, v27
	v_fma_f32 v3, -v68, v23, v3
	v_add_f32_e32 v3, v24, v3
	v_add_f32_e32 v24, v27, v25
	v_add_f32_e32 v24, v24, v3
	s_waitcnt lgkmcnt(5)
	v_fma_f32 v25, -v17, v33, 0
	v_add_u32_e32 v3, 0, v2
	ds_read_b128 v[28:31], v3 offset:6256
	ds_read_b128 v[40:43], v3 offset:6272
	ds_read_b128 v[48:51], v3 offset:6288
	ds_read_b128 v[52:55], v3 offset:6304
	ds_read_b128 v[60:63], v3 offset:6320
	s_waitcnt lgkmcnt(5)
	ds_read_b128 v[72:75], v3 offset:6336
	v_fma_f32 v3, -v195, v32, v217
	v_fma_f32 v27, -v15, v34, 0
	v_fma_f32 v32, -v13, v35, 0
	v_fma_f32 v3, -v11, v36, v3
	v_fma_f32 v25, -v9, v37, v25
	v_fma_f32 v27, -v7, v38, v27
	v_fma_f32 v32, -v4, v39, v32
	v_fma_f32 v3, -v5, v44, v3
	v_fma_f32 v25, -v6, v45, v25
	v_fma_f32 v27, -v8, v46, v27
	v_fma_f32 v32, -v10, v47, v32
	v_fma_f32 v3, -v12, v56, v3
	v_fma_f32 v25, -v14, v57, v25
	v_fma_f32 v27, -v16, v58, v27
	v_fma_f32 v32, -v18, v59, v32
	v_fma_f32 v3, -v19, v64, v3
	v_fma_f32 v25, -v20, v65, v25
	v_fma_f32 v27, -v21, v66, v27
	v_fma_f32 v32, -v22, v67, v32
	v_fma_f32 v3, -v23, v70, v3
	v_fma_f32 v25, -v71, v24, v25
	v_add_f32_e32 v3, v25, v3
	v_add_f32_e32 v25, v32, v27
	v_add_f32_e32 v25, v25, v3
	s_waitcnt lgkmcnt(5)
	v_fma_f32 v27, -v17, v29, 0
	v_add_u32_e32 v3, 0, v2
	ds_read_b128 v[32:35], v3 offset:6528
	ds_read_b128 v[36:39], v3 offset:6544
	ds_read_b128 v[44:47], v3 offset:6560
	ds_read_b128 v[56:59], v3 offset:6576
	ds_read_b128 v[64:67], v3 offset:6592
	ds_read_b128 v[68:71], v3 offset:6608
	v_fma_f32 v3, -v195, v28, v218
	v_fma_f32 v28, -v15, v30, 0
	v_fma_f32 v29, -v13, v31, 0
	s_waitcnt lgkmcnt(10)
	v_fma_f32 v3, -v11, v40, v3
	v_fma_f32 v27, -v9, v41, v27
	v_fma_f32 v28, -v7, v42, v28
	v_fma_f32 v29, -v4, v43, v29
	s_waitcnt lgkmcnt(9)
	v_fma_f32 v3, -v5, v48, v3
	v_fma_f32 v27, -v6, v49, v27
	v_fma_f32 v28, -v8, v50, v28
	v_fma_f32 v29, -v10, v51, v29
	s_waitcnt lgkmcnt(8)
	v_fma_f32 v3, -v12, v52, v3
	v_fma_f32 v27, -v14, v53, v27
	v_fma_f32 v28, -v16, v54, v28
	v_fma_f32 v29, -v18, v55, v29
	s_waitcnt lgkmcnt(7)
	v_fma_f32 v3, -v19, v60, v3
	v_fma_f32 v27, -v20, v61, v27
	v_fma_f32 v28, -v21, v62, v28
	v_fma_f32 v29, -v22, v63, v29
	s_waitcnt lgkmcnt(6)
	v_fma_f32 v3, -v23, v72, v3
	v_fma_f32 v27, -v24, v73, v27
	v_fma_f32 v28, -v74, v25, v28
	v_add_f32_e32 v3, v27, v3
	v_add_f32_e32 v27, v29, v28
	v_add_f32_e32 v27, v27, v3
	s_waitcnt lgkmcnt(5)
	v_fma_f32 v28, -v17, v33, 0
	v_add_u32_e32 v3, 0, v2
	ds_read_b128 v[40:43], v3 offset:6800
	ds_read_b128 v[48:51], v3 offset:6816
	ds_read_b128 v[52:55], v3 offset:6832
	ds_read_b128 v[60:63], v3 offset:6848
	ds_read_b128 v[72:75], v3 offset:6864
	ds_read_b128 v[76:79], v3 offset:6880
	ds_read_b128 v[140:143], v3 offset:6896
	v_fma_f32 v3, -v195, v32, v219
	v_fma_f32 v29, -v15, v34, 0
	v_fma_f32 v30, -v13, v35, 0
	s_waitcnt lgkmcnt(11)
	v_fma_f32 v3, -v11, v36, v3
	v_fma_f32 v28, -v9, v37, v28
	v_fma_f32 v29, -v7, v38, v29
	v_fma_f32 v30, -v4, v39, v30
	s_waitcnt lgkmcnt(10)
	v_fma_f32 v3, -v5, v44, v3
	v_fma_f32 v28, -v6, v45, v28
	v_fma_f32 v29, -v8, v46, v29
	v_fma_f32 v30, -v10, v47, v30
	s_waitcnt lgkmcnt(9)
	v_fma_f32 v3, -v12, v56, v3
	v_fma_f32 v28, -v14, v57, v28
	v_fma_f32 v29, -v16, v58, v29
	v_fma_f32 v30, -v18, v59, v30
	s_waitcnt lgkmcnt(8)
	v_fma_f32 v3, -v19, v64, v3
	v_fma_f32 v28, -v20, v65, v28
	v_fma_f32 v29, -v21, v66, v29
	v_fma_f32 v30, -v22, v67, v30
	s_waitcnt lgkmcnt(7)
	v_fma_f32 v3, -v23, v68, v3
	v_fma_f32 v28, -v24, v69, v28
	v_fma_f32 v29, -v25, v70, v29
	v_fma_f32 v30, -v71, v27, v30
	v_add_f32_e32 v3, v28, v3
	v_add_f32_e32 v28, v30, v29
	v_add_f32_e32 v28, v28, v3
	s_waitcnt lgkmcnt(6)
	v_fma_f32 v29, -v17, v41, 0
	v_add_u32_e32 v3, 0, v2
	ds_read_b128 v[30:33], v3 offset:7072
	ds_read_b128 v[34:37], v3 offset:7088
	ds_read_b128 v[44:47], v3 offset:7104
	ds_read_b128 v[56:59], v3 offset:7120
	ds_read_b128 v[64:67], v3 offset:7136
	ds_read_b128 v[68:71], v3 offset:7152
	s_waitcnt lgkmcnt(6)
	ds_read_b128 v[142:145], v3 offset:7168
	v_fma_f32 v3, -v195, v40, v220
	v_fma_f32 v38, -v15, v42, 0
	v_fma_f32 v39, -v13, v43, 0
	v_fma_f32 v3, -v11, v48, v3
	v_fma_f32 v29, -v9, v49, v29
	v_fma_f32 v38, -v7, v50, v38
	v_fma_f32 v39, -v4, v51, v39
	v_fma_f32 v3, -v5, v52, v3
	v_fma_f32 v29, -v6, v53, v29
	v_fma_f32 v38, -v8, v54, v38
	v_fma_f32 v39, -v10, v55, v39
	v_fma_f32 v3, -v12, v60, v3
	v_fma_f32 v29, -v14, v61, v29
	v_fma_f32 v38, -v16, v62, v38
	v_fma_f32 v39, -v18, v63, v39
	v_fma_f32 v3, -v19, v72, v3
	v_fma_f32 v29, -v20, v73, v29
	v_fma_f32 v38, -v21, v74, v38
	v_fma_f32 v39, -v22, v75, v39
	v_fma_f32 v3, -v23, v76, v3
	v_fma_f32 v29, -v24, v77, v29
	v_fma_f32 v38, -v25, v78, v38
	v_fma_f32 v39, -v27, v79, v39
	v_fma_f32 v3, -v140, v28, v3
	v_add_f32_e32 v3, v29, v3
	v_add_f32_e32 v29, v39, v38
	v_add_f32_e32 v29, v29, v3
	s_nop 0
	v_add_u32_e32 v3, 0, v2
	ds_read_b128 v[38:41], v3 offset:7344
	ds_read_b128 v[48:51], v3 offset:7360
	ds_read_b128 v[52:55], v3 offset:7376
	ds_read_b128 v[60:63], v3 offset:7392
	ds_read_b128 v[72:75], v3 offset:7408
	ds_read_b128 v[76:79], v3 offset:7424
	s_waitcnt lgkmcnt(6)
	ds_read_b128 v[144:147], v3 offset:7440
	v_fma_f32 v3, -v195, v30, v221
	v_fma_f32 v30, -v17, v31, 0
	v_fma_f32 v31, -v15, v32, 0
	v_fma_f32 v32, -v13, v33, 0
	v_fma_f32 v3, -v11, v34, v3
	v_fma_f32 v30, -v9, v35, v30
	v_fma_f32 v31, -v7, v36, v31
	v_fma_f32 v32, -v4, v37, v32
	v_fma_f32 v3, -v5, v44, v3
	v_fma_f32 v30, -v6, v45, v30
	v_fma_f32 v31, -v8, v46, v31
	v_fma_f32 v32, -v10, v47, v32
	v_fma_f32 v3, -v12, v56, v3
	v_fma_f32 v30, -v14, v57, v30
	v_fma_f32 v31, -v16, v58, v31
	v_fma_f32 v32, -v18, v59, v32
	v_fma_f32 v3, -v19, v64, v3
	v_fma_f32 v30, -v20, v65, v30
	v_fma_f32 v31, -v21, v66, v31
	v_fma_f32 v32, -v22, v67, v32
	v_fma_f32 v3, -v23, v68, v3
	v_fma_f32 v30, -v24, v69, v30
	v_fma_f32 v31, -v25, v70, v31
	v_fma_f32 v32, -v27, v71, v32
	v_fma_f32 v3, -v28, v142, v3
	v_fma_f32 v30, -v143, v29, v30
	v_add_f32_e32 v3, v30, v3
	v_add_f32_e32 v30, v32, v31
	v_add_f32_e32 v30, v30, v3
	s_waitcnt lgkmcnt(6)
	v_fma_f32 v31, -v17, v39, 0
	v_add_u32_e32 v3, 0, v2
	ds_read_b128 v[32:35], v3 offset:7616
	ds_read_b128 v[42:45], v3 offset:7632
	ds_read_b128 v[56:59], v3 offset:7648
	ds_read_b128 v[64:67], v3 offset:7664
	ds_read_b128 v[68:71], v3 offset:7680
	ds_read_b128 v[140:143], v3 offset:7696
	ds_read_b128 v[148:151], v3 offset:7712
	v_fma_f32 v3, -v195, v38, v222
	v_fma_f32 v36, -v15, v40, 0
	v_fma_f32 v37, -v13, v41, 0
	s_waitcnt lgkmcnt(12)
	v_fma_f32 v3, -v11, v48, v3
	v_fma_f32 v31, -v9, v49, v31
	v_fma_f32 v36, -v7, v50, v36
	v_fma_f32 v37, -v4, v51, v37
	s_waitcnt lgkmcnt(11)
	v_fma_f32 v3, -v5, v52, v3
	v_fma_f32 v31, -v6, v53, v31
	v_fma_f32 v36, -v8, v54, v36
	v_fma_f32 v37, -v10, v55, v37
	s_waitcnt lgkmcnt(10)
	v_fma_f32 v3, -v12, v60, v3
	v_fma_f32 v31, -v14, v61, v31
	v_fma_f32 v36, -v16, v62, v36
	v_fma_f32 v37, -v18, v63, v37
	s_waitcnt lgkmcnt(9)
	v_fma_f32 v3, -v19, v72, v3
	v_fma_f32 v31, -v20, v73, v31
	v_fma_f32 v36, -v21, v74, v36
	v_fma_f32 v37, -v22, v75, v37
	s_waitcnt lgkmcnt(8)
	v_fma_f32 v3, -v23, v76, v3
	v_fma_f32 v31, -v24, v77, v31
	v_fma_f32 v36, -v25, v78, v36
	v_fma_f32 v37, -v27, v79, v37
	s_waitcnt lgkmcnt(7)
	v_fma_f32 v3, -v28, v144, v3
	v_fma_f32 v31, -v29, v145, v31
	v_fma_f32 v36, -v146, v30, v36
	v_add_f32_e32 v3, v31, v3
	v_add_f32_e32 v31, v37, v36
	v_add_f32_e32 v31, v31, v3
	s_nop 0
	v_add_u32_e32 v3, 0, v2
	ds_read_b128 v[36:39], v3 offset:7888
	ds_read_b128 v[46:49], v3 offset:7904
	ds_read_b128 v[50:53], v3 offset:7920
	ds_read_b128 v[60:63], v3 offset:7936
	ds_read_b128 v[72:75], v3 offset:7952
	ds_read_b128 v[76:79], v3 offset:7968
	ds_read_b128 v[144:147], v3 offset:7984
	ds_read_b128 v[152:155], v3 offset:8000
	s_waitcnt lgkmcnt(14)
	v_fma_f32 v3, -v195, v32, v223
	v_fma_f32 v32, -v17, v33, 0
	v_fma_f32 v33, -v15, v34, 0
	v_fma_f32 v34, -v13, v35, 0
	s_waitcnt lgkmcnt(13)
	v_fma_f32 v3, -v11, v42, v3
	v_fma_f32 v32, -v9, v43, v32
	v_fma_f32 v33, -v7, v44, v33
	v_fma_f32 v34, -v4, v45, v34
	s_waitcnt lgkmcnt(12)
	v_fma_f32 v3, -v5, v56, v3
	v_fma_f32 v32, -v6, v57, v32
	v_fma_f32 v33, -v8, v58, v33
	v_fma_f32 v34, -v10, v59, v34
	s_waitcnt lgkmcnt(11)
	v_fma_f32 v3, -v12, v64, v3
	v_fma_f32 v32, -v14, v65, v32
	v_fma_f32 v33, -v16, v66, v33
	v_fma_f32 v34, -v18, v67, v34
	s_waitcnt lgkmcnt(10)
	v_fma_f32 v3, -v19, v68, v3
	v_fma_f32 v32, -v20, v69, v32
	v_fma_f32 v33, -v21, v70, v33
	v_fma_f32 v34, -v22, v71, v34
	s_waitcnt lgkmcnt(9)
	v_fma_f32 v3, -v23, v140, v3
	v_fma_f32 v32, -v24, v141, v32
	v_fma_f32 v33, -v25, v142, v33
	v_fma_f32 v34, -v27, v143, v34
	s_waitcnt lgkmcnt(8)
	v_fma_f32 v3, -v28, v148, v3
	v_fma_f32 v32, -v29, v149, v32
	v_fma_f32 v33, -v30, v150, v33
	v_fma_f32 v34, -v151, v31, v34
	v_add_f32_e32 v3, v32, v3
	v_add_f32_e32 v32, v34, v33
	v_add_f32_e32 v32, v32, v3
	s_waitcnt lgkmcnt(7)
	v_fma_f32 v33, -v17, v37, 0
	v_add_u32_e32 v3, 0, v2
	ds_read_b128 v[40:43], v3 offset:8160
	ds_read_b128 v[54:57], v3 offset:8176
	ds_read_b128 v[64:67], v3 offset:8192
	ds_read_b128 v[68:71], v3 offset:8208
	ds_read_b128 v[140:143], v3 offset:8224
	ds_read_b128 v[148:151], v3 offset:8240
	s_waitcnt lgkmcnt(6)
	ds_read_b128 v[154:157], v3 offset:8256
	ds_read_b128 v[158:161], v3 offset:8272
	v_fma_f32 v3, -v195, v36, v224
	v_fma_f32 v34, -v15, v38, 0
	v_fma_f32 v35, -v13, v39, 0
	v_fma_f32 v3, -v11, v46, v3
	v_fma_f32 v33, -v9, v47, v33
	v_fma_f32 v34, -v7, v48, v34
	v_fma_f32 v35, -v4, v49, v35
	v_fma_f32 v3, -v5, v50, v3
	v_fma_f32 v33, -v6, v51, v33
	v_fma_f32 v34, -v8, v52, v34
	v_fma_f32 v35, -v10, v53, v35
	v_fma_f32 v3, -v12, v60, v3
	v_fma_f32 v33, -v14, v61, v33
	v_fma_f32 v34, -v16, v62, v34
	v_fma_f32 v35, -v18, v63, v35
	v_fma_f32 v3, -v19, v72, v3
	v_fma_f32 v33, -v20, v73, v33
	v_fma_f32 v34, -v21, v74, v34
	v_fma_f32 v35, -v22, v75, v35
	v_fma_f32 v3, -v23, v76, v3
	v_fma_f32 v33, -v24, v77, v33
	v_fma_f32 v34, -v25, v78, v34
	v_fma_f32 v35, -v27, v79, v35
	v_fma_f32 v3, -v28, v144, v3
	v_fma_f32 v33, -v29, v145, v33
	v_fma_f32 v34, -v30, v146, v34
	v_fma_f32 v35, -v31, v147, v35
	v_fma_f32 v3, -v152, v32, v3
	v_add_f32_e32 v3, v33, v3
	v_add_f32_e32 v33, v35, v34
	v_add_f32_e32 v33, v33, v3
	s_waitcnt lgkmcnt(7)
	v_fma_f32 v34, -v17, v41, 0
	v_add_u32_e32 v3, 0, v2
	ds_read_b128 v[36:39], v3 offset:8432
	ds_read_b128 v[44:47], v3 offset:8448
	ds_read_b128 v[48:51], v3 offset:8464
	ds_read_b128 v[58:61], v3 offset:8480
	ds_read_b128 v[72:75], v3 offset:8496
	ds_read_b128 v[76:79], v3 offset:8512
	ds_read_b128 v[144:147], v3 offset:8528
	s_waitcnt lgkmcnt(7)
	ds_read_b128 v[160:163], v3 offset:8544
	v_fma_f32 v3, -v195, v40, v225
	v_fma_f32 v35, -v15, v42, 0
	v_fma_f32 v40, -v13, v43, 0
	v_fma_f32 v3, -v11, v54, v3
	v_fma_f32 v34, -v9, v55, v34
	v_fma_f32 v35, -v7, v56, v35
	v_fma_f32 v40, -v4, v57, v40
	v_fma_f32 v3, -v5, v64, v3
	v_fma_f32 v34, -v6, v65, v34
	v_fma_f32 v35, -v8, v66, v35
	v_fma_f32 v40, -v10, v67, v40
	v_fma_f32 v3, -v12, v68, v3
	v_fma_f32 v34, -v14, v69, v34
	v_fma_f32 v35, -v16, v70, v35
	v_fma_f32 v40, -v18, v71, v40
	v_fma_f32 v3, -v19, v140, v3
	v_fma_f32 v34, -v20, v141, v34
	v_fma_f32 v35, -v21, v142, v35
	v_fma_f32 v40, -v22, v143, v40
	v_fma_f32 v3, -v23, v148, v3
	v_fma_f32 v34, -v24, v149, v34
	v_fma_f32 v35, -v25, v150, v35
	v_fma_f32 v40, -v27, v151, v40
	v_fma_f32 v3, -v28, v154, v3
	v_fma_f32 v34, -v29, v155, v34
	v_fma_f32 v35, -v30, v156, v35
	v_fma_f32 v40, -v31, v157, v40
	v_fma_f32 v3, -v32, v158, v3
	v_fma_f32 v34, -v159, v33, v34
	v_add_f32_e32 v3, v34, v3
	v_add_f32_e32 v34, v40, v35
	v_add_f32_e32 v34, v34, v3
	s_waitcnt lgkmcnt(7)
	v_fma_f32 v3, -v17, v37, 0
	v_fma_f32 v2, -v195, v36, v226
	v_fma_f32 v35, -v15, v38, 0
	v_fma_f32 v36, -v13, v39, 0
	s_waitcnt lgkmcnt(6)
	v_fma_f32 v2, -v11, v44, v2
	v_fma_f32 v3, -v9, v45, v3
	v_fma_f32 v35, -v7, v46, v35
	v_fma_f32 v36, -v4, v47, v36
	s_waitcnt lgkmcnt(5)
	v_fma_f32 v2, -v5, v48, v2
	v_fma_f32 v3, -v6, v49, v3
	v_fma_f32 v35, -v8, v50, v35
	v_fma_f32 v36, -v10, v51, v36
	s_waitcnt lgkmcnt(4)
	v_fma_f32 v2, -v12, v58, v2
	v_fma_f32 v3, -v14, v59, v3
	v_fma_f32 v35, -v16, v60, v35
	v_fma_f32 v36, -v18, v61, v36
	s_waitcnt lgkmcnt(3)
	v_fma_f32 v2, -v19, v72, v2
	v_fma_f32 v3, -v20, v73, v3
	v_fma_f32 v35, -v21, v74, v35
	v_fma_f32 v36, -v22, v75, v36
	s_waitcnt lgkmcnt(2)
	v_fma_f32 v2, -v23, v76, v2
	v_fma_f32 v3, -v24, v77, v3
	v_fma_f32 v35, -v25, v78, v35
	v_fma_f32 v36, -v27, v79, v36
	s_waitcnt lgkmcnt(1)
	v_fma_f32 v2, -v28, v144, v2
	v_fma_f32 v3, -v29, v145, v3
	v_fma_f32 v35, -v30, v146, v35
	v_fma_f32 v36, -v31, v147, v36
	s_waitcnt lgkmcnt(0)
	v_fma_f32 v2, -v32, v160, v2
	v_fma_f32 v3, -v33, v161, v3
	v_fma_f32 v35, -v162, v34, v35
	v_add_f32_e32 v2, v3, v2
	v_add_f32_e32 v3, v36, v35
	v_add_f32_e32 v35, v3, v2
	ds_read2st64_b32 v[2:3], v186 offset1:2
	s_waitcnt lgkmcnt(0)
	v_mul_f32_e32 v36, v2, v3
	v_mul_f32_e32 v3, v195, v2
	v_cvt_pk_bf16_f32 v3, v3, v3
	ds_write_b16 v190, v3
	v_mul_f32_e32 v3, v195, v36
	v_cvt_pk_bf16_f32 v3, v3, v3
	ds_write_b16 v190, v3 offset:64
	v_add_u32_e32 v3, v171, v189
	s_and_saveexec_b64 s[18:19], s[8:9]
	ds_write_b16 v3, v227 offset:128
	s_or_b64 exec, exec, s[18:19]
	v_mul_f32_e32 v37, v17, v2
	v_cvt_pk_bf16_f32 v37, v37, v37
	ds_write_b16 v190, v37 offset:272
	v_mul_f32_e32 v37, v17, v36
	v_bfe_u32 v38, v37, 16, 1
	v_add3_u32 v37, v37, v38, s54
	ds_write_b16_d16_hi v190, v37 offset:336
	s_and_saveexec_b64 s[18:19], s[8:9]
	v_xor_b32_e32 v17, 0x80000000, v17
	v_cvt_pk_bf16_f32 v17, v17, v17
	ds_write_b16 v3, v17 offset:400
	s_or_b64 exec, exec, s[18:19]
	v_mul_f32_e32 v17, v15, v2
	v_cvt_pk_bf16_f32 v17, v17, v17
	ds_write_b16 v190, v17 offset:544
	v_mul_f32_e32 v17, v15, v36
	v_bfe_u32 v37, v17, 16, 1
	v_add3_u32 v17, v17, v37, s54
	ds_write_b16_d16_hi v190, v17 offset:608
	s_and_saveexec_b64 s[18:19], s[8:9]
	v_xor_b32_e32 v15, 0x80000000, v15
	v_cvt_pk_bf16_f32 v15, v15, v15
	ds_write_b16 v3, v15 offset:672
	s_or_b64 exec, exec, s[18:19]
	v_mul_f32_e32 v15, v13, v2
	v_cvt_pk_bf16_f32 v15, v15, v15
	ds_write_b16 v190, v15 offset:816
	v_mul_f32_e32 v15, v13, v36
	v_bfe_u32 v17, v15, 16, 1
	v_add3_u32 v15, v15, v17, s54
	ds_write_b16_d16_hi v190, v15 offset:880
	s_and_saveexec_b64 s[18:19], s[8:9]
	v_xor_b32_e32 v13, 0x80000000, v13
	v_cvt_pk_bf16_f32 v13, v13, v13
	ds_write_b16 v3, v13 offset:944
	s_or_b64 exec, exec, s[18:19]
	v_mul_f32_e32 v13, v11, v2
	v_cvt_pk_bf16_f32 v13, v13, v13
	ds_write_b16 v190, v13 offset:1088
	v_mul_f32_e32 v13, v11, v36
	v_bfe_u32 v15, v13, 16, 1
	v_add3_u32 v13, v13, v15, s54
	ds_write_b16_d16_hi v190, v13 offset:1152
	s_and_saveexec_b64 s[18:19], s[8:9]
	v_xor_b32_e32 v11, 0x80000000, v11
	v_cvt_pk_bf16_f32 v11, v11, v11
	ds_write_b16 v3, v11 offset:1216
	s_or_b64 exec, exec, s[18:19]
	v_mul_f32_e32 v11, v9, v2
	v_cvt_pk_bf16_f32 v11, v11, v11
	ds_write_b16 v190, v11 offset:1360
	v_mul_f32_e32 v11, v9, v36
	v_bfe_u32 v13, v11, 16, 1
	v_add3_u32 v11, v11, v13, s54
	ds_write_b16_d16_hi v190, v11 offset:1424
	s_and_saveexec_b64 s[18:19], s[8:9]
	v_xor_b32_e32 v9, 0x80000000, v9
	v_cvt_pk_bf16_f32 v9, v9, v9
	ds_write_b16 v3, v9 offset:1488
	s_or_b64 exec, exec, s[18:19]
	v_mul_f32_e32 v9, v7, v2
	v_cvt_pk_bf16_f32 v9, v9, v9
	ds_write_b16 v190, v9 offset:1632
	v_mul_f32_e32 v9, v7, v36
	v_bfe_u32 v11, v9, 16, 1
	v_add3_u32 v9, v9, v11, s54
	ds_write_b16_d16_hi v190, v9 offset:1696
	s_and_saveexec_b64 s[18:19], s[8:9]
	v_xor_b32_e32 v7, 0x80000000, v7
	v_cvt_pk_bf16_f32 v7, v7, v7
	ds_write_b16 v3, v7 offset:1760
	s_or_b64 exec, exec, s[18:19]
	v_mul_f32_e32 v7, v4, v2
	v_cvt_pk_bf16_f32 v7, v7, v7
	ds_write_b16 v190, v7 offset:1904
	v_mul_f32_e32 v7, v4, v36
	v_bfe_u32 v9, v7, 16, 1
	v_add3_u32 v7, v7, v9, s54
	ds_write_b16_d16_hi v190, v7 offset:1968
	s_and_saveexec_b64 s[18:19], s[8:9]
	v_xor_b32_e32 v4, 0x80000000, v4
	v_cvt_pk_bf16_f32 v4, v4, v4
	ds_write_b16 v3, v4 offset:2032
	s_or_b64 exec, exec, s[18:19]
	v_mul_f32_e32 v4, v5, v2
	v_cvt_pk_bf16_f32 v4, v4, v4
	ds_write_b16 v190, v4 offset:2176
	v_mul_f32_e32 v4, v5, v36
	v_bfe_u32 v7, v4, 16, 1
	v_add3_u32 v4, v4, v7, s54
	ds_write_b16_d16_hi v190, v4 offset:2240
	s_and_saveexec_b64 s[18:19], s[8:9]
	v_xor_b32_e32 v4, 0x80000000, v5
	v_cvt_pk_bf16_f32 v4, v4, v4
	ds_write_b16 v3, v4 offset:2304
	s_or_b64 exec, exec, s[18:19]
	v_mul_f32_e32 v4, v6, v2
	v_cvt_pk_bf16_f32 v4, v4, v4
	ds_write_b16 v190, v4 offset:2448
	v_mul_f32_e32 v4, v6, v36
	v_cvt_pk_bf16_f32 v4, v4, v4
	ds_write_b16 v190, v4 offset:2512
	s_and_saveexec_b64 s[18:19], s[8:9]
	v_xor_b32_e32 v4, 0x80000000, v6
	v_cvt_pk_bf16_f32 v4, v4, v4
	ds_write_b16 v3, v4 offset:2576
	s_or_b64 exec, exec, s[18:19]
	v_mul_f32_e32 v4, v8, v2
	v_cvt_pk_bf16_f32 v4, v4, v4
	ds_write_b16 v190, v4 offset:2720
	v_mul_f32_e32 v4, v8, v36
	v_cvt_pk_bf16_f32 v4, v4, v4
	ds_write_b16 v190, v4 offset:2784
	s_and_saveexec_b64 s[18:19], s[8:9]
	v_xor_b32_e32 v4, 0x80000000, v8
	v_cvt_pk_bf16_f32 v4, v4, v4
	ds_write_b16 v3, v4 offset:2848
	s_or_b64 exec, exec, s[18:19]
	v_mul_f32_e32 v4, v10, v2
	v_cvt_pk_bf16_f32 v4, v4, v4
	ds_write_b16 v190, v4 offset:2992
	v_mul_f32_e32 v4, v10, v36
	v_cvt_pk_bf16_f32 v4, v4, v4
	ds_write_b16 v190, v4 offset:3056
	s_and_saveexec_b64 s[18:19], s[8:9]
	v_xor_b32_e32 v4, 0x80000000, v10
	v_cvt_pk_bf16_f32 v4, v4, v4
	ds_write_b16 v3, v4 offset:3120
	s_or_b64 exec, exec, s[18:19]
	v_mul_f32_e32 v4, v12, v2
	v_cvt_pk_bf16_f32 v4, v4, v4
	ds_write_b16 v190, v4 offset:3264
	v_mul_f32_e32 v4, v12, v36
	v_cvt_pk_bf16_f32 v4, v4, v4
	ds_write_b16 v190, v4 offset:3328
	s_and_saveexec_b64 s[18:19], s[8:9]
	v_xor_b32_e32 v4, 0x80000000, v12
	v_cvt_pk_bf16_f32 v4, v4, v4
	ds_write_b16 v3, v4 offset:3392
	s_or_b64 exec, exec, s[18:19]
	v_mul_f32_e32 v4, v14, v2
	v_cvt_pk_bf16_f32 v4, v4, v4
	ds_write_b16 v190, v4 offset:3536
	v_mul_f32_e32 v4, v14, v36
	v_cvt_pk_bf16_f32 v4, v4, v4
	ds_write_b16 v190, v4 offset:3600
	s_and_saveexec_b64 s[18:19], s[8:9]
	v_xor_b32_e32 v4, 0x80000000, v14
	v_cvt_pk_bf16_f32 v4, v4, v4
	ds_write_b16 v3, v4 offset:3664
	s_or_b64 exec, exec, s[18:19]
	v_mul_f32_e32 v4, v16, v2
	v_cvt_pk_bf16_f32 v4, v4, v4
	ds_write_b16 v190, v4 offset:3808
	v_mul_f32_e32 v4, v16, v36
	v_cvt_pk_bf16_f32 v4, v4, v4
	ds_write_b16 v190, v4 offset:3872
	s_and_saveexec_b64 s[18:19], s[8:9]
	v_xor_b32_e32 v4, 0x80000000, v16
	v_cvt_pk_bf16_f32 v4, v4, v4
	ds_write_b16 v3, v4 offset:3936
	s_or_b64 exec, exec, s[18:19]
	v_mul_f32_e32 v4, v18, v2
	v_cvt_pk_bf16_f32 v4, v4, v4
	ds_write_b16 v190, v4 offset:4080
	v_mul_f32_e32 v4, v18, v36
	v_cvt_pk_bf16_f32 v4, v4, v4
	ds_write_b16 v190, v4 offset:4144
	s_and_saveexec_b64 s[18:19], s[8:9]
	v_xor_b32_e32 v4, 0x80000000, v18
	v_cvt_pk_bf16_f32 v4, v4, v4
	ds_write_b16 v3, v4 offset:4208
	s_or_b64 exec, exec, s[18:19]
	v_mul_f32_e32 v4, v19, v2
	v_cvt_pk_bf16_f32 v4, v4, v4
	ds_write_b16 v190, v4 offset:4352
	v_mul_f32_e32 v4, v19, v36
	v_cvt_pk_bf16_f32 v4, v4, v4
	ds_write_b16 v190, v4 offset:4416
	s_and_saveexec_b64 s[18:19], s[8:9]
	v_xor_b32_e32 v4, 0x80000000, v19
	v_cvt_pk_bf16_f32 v4, v4, v4
	ds_write_b16 v3, v4 offset:4480
	s_or_b64 exec, exec, s[18:19]
	v_mul_f32_e32 v4, v20, v2
	v_cvt_pk_bf16_f32 v4, v4, v4
	ds_write_b16 v190, v4 offset:4624
	v_mul_f32_e32 v4, v20, v36
	v_cvt_pk_bf16_f32 v4, v4, v4
	ds_write_b16 v190, v4 offset:4688
	s_and_saveexec_b64 s[18:19], s[8:9]
	v_xor_b32_e32 v4, 0x80000000, v20
	v_cvt_pk_bf16_f32 v4, v4, v4
	ds_write_b16 v3, v4 offset:4752
	s_or_b64 exec, exec, s[18:19]
	v_mul_f32_e32 v4, v21, v2
	v_cvt_pk_bf16_f32 v4, v4, v4
	ds_write_b16 v190, v4 offset:4896
	v_mul_f32_e32 v4, v21, v36
	v_cvt_pk_bf16_f32 v4, v4, v4
	ds_write_b16 v190, v4 offset:4960
	s_and_saveexec_b64 s[18:19], s[8:9]
	v_xor_b32_e32 v4, 0x80000000, v21
	v_cvt_pk_bf16_f32 v4, v4, v4
	ds_write_b16 v3, v4 offset:5024
	s_or_b64 exec, exec, s[18:19]
	v_mul_f32_e32 v4, v22, v2
	v_cvt_pk_bf16_f32 v4, v4, v4
	ds_write_b16 v190, v4 offset:5168
	v_mul_f32_e32 v4, v22, v36
	v_cvt_pk_bf16_f32 v4, v4, v4
	ds_write_b16 v190, v4 offset:5232
	s_and_saveexec_b64 s[18:19], s[8:9]
	v_xor_b32_e32 v4, 0x80000000, v22
	v_cvt_pk_bf16_f32 v4, v4, v4
	ds_write_b16 v3, v4 offset:5296
	s_or_b64 exec, exec, s[18:19]
	v_mul_f32_e32 v4, v23, v2
	v_cvt_pk_bf16_f32 v4, v4, v4
	ds_write_b16 v190, v4 offset:5440
	v_mul_f32_e32 v4, v23, v36
	v_cvt_pk_bf16_f32 v4, v4, v4
	ds_write_b16 v190, v4 offset:5504
	s_and_saveexec_b64 s[18:19], s[8:9]
	v_xor_b32_e32 v4, 0x80000000, v23
	v_cvt_pk_bf16_f32 v4, v4, v4
	ds_write_b16 v3, v4 offset:5568
	s_or_b64 exec, exec, s[18:19]
	v_mul_f32_e32 v4, v24, v2
	v_cvt_pk_bf16_f32 v4, v4, v4
	ds_write_b16 v190, v4 offset:5712
	v_mul_f32_e32 v4, v24, v36
	v_cvt_pk_bf16_f32 v4, v4, v4
	ds_write_b16 v190, v4 offset:5776
	s_and_saveexec_b64 s[18:19], s[8:9]
	v_xor_b32_e32 v4, 0x80000000, v24
	v_cvt_pk_bf16_f32 v4, v4, v4
	ds_write_b16 v3, v4 offset:5840
	s_or_b64 exec, exec, s[18:19]
	v_mul_f32_e32 v4, v25, v2
	v_cvt_pk_bf16_f32 v4, v4, v4
	ds_write_b16 v190, v4 offset:5984
	v_mul_f32_e32 v4, v25, v36
	v_cvt_pk_bf16_f32 v4, v4, v4
	ds_write_b16 v190, v4 offset:6048
	s_and_saveexec_b64 s[18:19], s[8:9]
	v_xor_b32_e32 v4, 0x80000000, v25
	v_cvt_pk_bf16_f32 v4, v4, v4
	ds_write_b16 v3, v4 offset:6112
	s_or_b64 exec, exec, s[18:19]
	v_mul_f32_e32 v4, v27, v2
	v_cvt_pk_bf16_f32 v4, v4, v4
	ds_write_b16 v190, v4 offset:6256
	v_mul_f32_e32 v4, v27, v36
	v_cvt_pk_bf16_f32 v4, v4, v4
	ds_write_b16 v190, v4 offset:6320
	s_and_saveexec_b64 s[18:19], s[8:9]
	v_xor_b32_e32 v4, 0x80000000, v27
	v_cvt_pk_bf16_f32 v4, v4, v4
	ds_write_b16 v3, v4 offset:6384
	s_or_b64 exec, exec, s[18:19]
	v_mul_f32_e32 v4, v28, v2
	v_cvt_pk_bf16_f32 v4, v4, v4
	ds_write_b16 v190, v4 offset:6528
	v_mul_f32_e32 v4, v28, v36
	v_cvt_pk_bf16_f32 v4, v4, v4
	ds_write_b16 v190, v4 offset:6592
	s_and_saveexec_b64 s[18:19], s[8:9]
	v_xor_b32_e32 v4, 0x80000000, v28
	v_cvt_pk_bf16_f32 v4, v4, v4
	ds_write_b16 v3, v4 offset:6656
	s_or_b64 exec, exec, s[18:19]
	v_mul_f32_e32 v4, v29, v2
	v_cvt_pk_bf16_f32 v4, v4, v4
	ds_write_b16 v190, v4 offset:6800
	v_mul_f32_e32 v4, v29, v36
	v_cvt_pk_bf16_f32 v4, v4, v4
	ds_write_b16 v190, v4 offset:6864
	s_and_saveexec_b64 s[18:19], s[8:9]
	v_xor_b32_e32 v4, 0x80000000, v29
	v_cvt_pk_bf16_f32 v4, v4, v4
	ds_write_b16 v3, v4 offset:6928
	s_or_b64 exec, exec, s[18:19]
	v_mul_f32_e32 v4, v30, v2
	v_cvt_pk_bf16_f32 v4, v4, v4
	ds_write_b16 v190, v4 offset:7072
	v_mul_f32_e32 v4, v30, v36
	v_cvt_pk_bf16_f32 v4, v4, v4
	ds_write_b16 v190, v4 offset:7136
	s_and_saveexec_b64 s[18:19], s[8:9]
	v_xor_b32_e32 v4, 0x80000000, v30
	v_cvt_pk_bf16_f32 v4, v4, v4
	ds_write_b16 v3, v4 offset:7200
	s_or_b64 exec, exec, s[18:19]
	v_mul_f32_e32 v4, v31, v2
	v_cvt_pk_bf16_f32 v4, v4, v4
	ds_write_b16 v190, v4 offset:7344
	v_mul_f32_e32 v4, v31, v36
	v_cvt_pk_bf16_f32 v4, v4, v4
	ds_write_b16 v190, v4 offset:7408
	s_and_saveexec_b64 s[18:19], s[8:9]
	v_xor_b32_e32 v4, 0x80000000, v31
	v_cvt_pk_bf16_f32 v4, v4, v4
	ds_write_b16 v3, v4 offset:7472
	s_or_b64 exec, exec, s[18:19]
	v_mul_f32_e32 v4, v32, v2
	v_cvt_pk_bf16_f32 v4, v4, v4
	ds_write_b16 v190, v4 offset:7616
	v_mul_f32_e32 v4, v32, v36
	v_cvt_pk_bf16_f32 v4, v4, v4
	ds_write_b16 v190, v4 offset:7680
	s_and_saveexec_b64 s[18:19], s[8:9]
	v_xor_b32_e32 v4, 0x80000000, v32
	v_cvt_pk_bf16_f32 v4, v4, v4
	ds_write_b16 v3, v4 offset:7744
	s_or_b64 exec, exec, s[18:19]
	v_mul_f32_e32 v4, v33, v2
	v_cvt_pk_bf16_f32 v4, v4, v4
	ds_write_b16 v190, v4 offset:7888
	v_mul_f32_e32 v4, v33, v36
	v_cvt_pk_bf16_f32 v4, v4, v4
	ds_write_b16 v190, v4 offset:7952
	s_and_saveexec_b64 s[18:19], s[8:9]
	v_xor_b32_e32 v4, 0x80000000, v33
	v_cvt_pk_bf16_f32 v4, v4, v4
	ds_write_b16 v3, v4 offset:8016
	s_or_b64 exec, exec, s[18:19]
	v_mul_f32_e32 v4, v34, v2
	v_cvt_pk_bf16_f32 v4, v4, v4
	ds_write_b16 v190, v4 offset:8160
	v_mul_f32_e32 v4, v34, v36
	v_cvt_pk_bf16_f32 v4, v4, v4
	ds_write_b16 v190, v4 offset:8224
	s_and_saveexec_b64 s[18:19], s[8:9]
	v_xor_b32_e32 v4, 0x80000000, v34
	v_cvt_pk_bf16_f32 v4, v4, v4
	ds_write_b16 v3, v4 offset:8288
	s_or_b64 exec, exec, s[18:19]
	v_mul_f32_e32 v2, v35, v2
	v_cvt_pk_bf16_f32 v2, v2, v2
	ds_write_b16 v190, v2 offset:8432
	v_mul_f32_e32 v2, v35, v36
	v_cvt_pk_bf16_f32 v2, v2, v2
	ds_write_b16 v190, v2 offset:8496
	s_and_saveexec_b64 s[18:19], s[8:9]
	v_xor_b32_e32 v2, 0x80000000, v35
	v_cvt_pk_bf16_f32 v2, v2, v2
	ds_write_b16 v3, v2 offset:8560
	s_or_b64 exec, exec, s[18:19]

.LBB0_425:
	s_and_b64 vcc, exec, s[38:39]
	s_barrier
	s_cbranch_vccz .LBB0_313
	s_movk_i32 s18, 0x440
	v_mad_u64_u32 v[66:67], s[18:19], v234, s18, v[168:169]
	v_lshlrev_b32_e32 v67, 1, v233
	v_xor_b32_e32 v2, 0x80000000, v2
	v_add3_u32 v66, v66, v67, s11
	v_cvt_pk_bf16_f32 v2, v2, v2
	ds_write_b16 v66, v2 offset:35840
	v_xor_b32_e32 v2, 0x80000000, v3
	v_cvt_pk_bf16_f32 v2, v2, v2
	ds_write_b16 v66, v2 offset:36112
	v_xor_b32_e32 v2, 0x80000000, v4
	v_cvt_pk_bf16_f32 v2, v2, v2
	ds_write_b16 v66, v2 offset:36384
	v_xor_b32_e32 v2, 0x80000000, v5
	v_cvt_pk_bf16_f32 v2, v2, v2
	ds_write_b16 v66, v2 offset:36656
	v_xor_b32_e32 v2, 0x80000000, v6
	v_cvt_pk_bf16_f32 v2, v2, v2
	ds_write_b16 v66, v2 offset:38016
	v_xor_b32_e32 v2, 0x80000000, v7
	v_cvt_pk_bf16_f32 v2, v2, v2
	ds_write_b16 v66, v2 offset:38288
	v_xor_b32_e32 v2, 0x80000000, v8
	v_cvt_pk_bf16_f32 v2, v2, v2
	ds_write_b16 v66, v2 offset:38560
	v_xor_b32_e32 v2, 0x80000000, v9
	v_cvt_pk_bf16_f32 v2, v2, v2
	ds_write_b16 v66, v2 offset:38832
	v_xor_b32_e32 v2, 0x80000000, v10
	v_cvt_pk_bf16_f32 v2, v2, v2
	ds_write_b16 v66, v2 offset:40192
	v_xor_b32_e32 v2, 0x80000000, v11
	v_cvt_pk_bf16_f32 v2, v2, v2
	ds_write_b16 v66, v2 offset:40464
	v_xor_b32_e32 v2, 0x80000000, v12
	v_cvt_pk_bf16_f32 v2, v2, v2
	ds_write_b16 v66, v2 offset:40736
	v_xor_b32_e32 v2, 0x80000000, v13
	v_cvt_pk_bf16_f32 v2, v2, v2
	ds_write_b16 v66, v2 offset:41008
	v_xor_b32_e32 v2, 0x80000000, v14
	v_cvt_pk_bf16_f32 v2, v2, v2
	ds_write_b16 v66, v2 offset:42368
	v_xor_b32_e32 v2, 0x80000000, v15
	v_cvt_pk_bf16_f32 v2, v2, v2
	ds_write_b16 v66, v2 offset:42640
	v_xor_b32_e32 v2, 0x80000000, v16
	v_cvt_pk_bf16_f32 v2, v2, v2
	ds_write_b16 v66, v2 offset:42912
	v_xor_b32_e32 v2, 0x80000000, v17
	v_cvt_pk_bf16_f32 v2, v2, v2
	ds_write_b16 v66, v2 offset:43184
	v_xor_b32_e32 v2, 0x80000000, v18
	v_cvt_pk_bf16_f32 v2, v2, v2
	ds_write_b16 v66, v2 offset:44544
	v_xor_b32_e32 v2, 0x80000000, v19
	v_cvt_pk_bf16_f32 v2, v2, v2
	ds_write_b16 v66, v2 offset:44816
	v_xor_b32_e32 v2, 0x80000000, v20
	v_cvt_pk_bf16_f32 v2, v2, v2
	ds_write_b16 v66, v2 offset:45088
	v_xor_b32_e32 v2, 0x80000000, v21
	v_cvt_pk_bf16_f32 v2, v2, v2
	ds_write_b16 v66, v2 offset:45360
	v_xor_b32_e32 v2, 0x80000000, v22
	v_cvt_pk_bf16_f32 v2, v2, v2
	ds_write_b16 v66, v2 offset:46720
	v_xor_b32_e32 v2, 0x80000000, v23
	v_cvt_pk_bf16_f32 v2, v2, v2
	ds_write_b16 v66, v2 offset:46992
	v_xor_b32_e32 v2, 0x80000000, v24
	v_cvt_pk_bf16_f32 v2, v2, v2
	ds_write_b16 v66, v2 offset:47264
	v_xor_b32_e32 v2, 0x80000000, v25
	v_cvt_pk_bf16_f32 v2, v2, v2
	ds_write_b16 v66, v2 offset:47536
	v_xor_b32_e32 v2, 0x80000000, v26
	v_cvt_pk_bf16_f32 v2, v2, v2
	ds_write_b16 v66, v2 offset:48896
	v_xor_b32_e32 v2, 0x80000000, v27
	v_cvt_pk_bf16_f32 v2, v2, v2
	ds_write_b16 v66, v2 offset:49168
	v_xor_b32_e32 v2, 0x80000000, v28
	v_cvt_pk_bf16_f32 v2, v2, v2
	ds_write_b16 v66, v2 offset:49440
	v_xor_b32_e32 v2, 0x80000000, v29
	v_cvt_pk_bf16_f32 v2, v2, v2
	ds_write_b16 v66, v2 offset:49712
	v_xor_b32_e32 v2, 0x80000000, v30
	v_cvt_pk_bf16_f32 v2, v2, v2
	ds_write_b16 v66, v2 offset:51072
	v_xor_b32_e32 v2, 0x80000000, v31
	v_cvt_pk_bf16_f32 v2, v2, v2
	ds_write_b16 v66, v2 offset:51344
	v_xor_b32_e32 v2, 0x80000000, v32
	v_cvt_pk_bf16_f32 v2, v2, v2
	ds_write_b16 v66, v2 offset:51616
	v_xor_b32_e32 v2, 0x80000000, v33
	v_cvt_pk_bf16_f32 v2, v2, v2
	ds_write_b16 v66, v2 offset:51888
	v_xor_b32_e32 v2, 0x80000000, v50
	v_cvt_pk_bf16_f32 v2, v2, v2
	ds_write_b16 v66, v2 offset:35904
	v_xor_b32_e32 v2, 0x80000000, v51
	v_cvt_pk_bf16_f32 v2, v2, v2
	ds_write_b16 v66, v2 offset:36176
	v_xor_b32_e32 v2, 0x80000000, v52
	v_cvt_pk_bf16_f32 v2, v2, v2
	ds_write_b16 v66, v2 offset:36448
	v_xor_b32_e32 v2, 0x80000000, v53
	v_cvt_pk_bf16_f32 v2, v2, v2
	ds_write_b16 v66, v2 offset:36720
	v_xor_b32_e32 v2, 0x80000000, v54
	v_cvt_pk_bf16_f32 v2, v2, v2
	ds_write_b16 v66, v2 offset:38080
	v_xor_b32_e32 v2, 0x80000000, v55
	v_cvt_pk_bf16_f32 v2, v2, v2
	ds_write_b16 v66, v2 offset:38352
	v_xor_b32_e32 v2, 0x80000000, v56
	v_cvt_pk_bf16_f32 v2, v2, v2
	ds_write_b16 v66, v2 offset:38624
	v_xor_b32_e32 v2, 0x80000000, v57
	v_cvt_pk_bf16_f32 v2, v2, v2
	ds_write_b16 v66, v2 offset:38896
	v_xor_b32_e32 v2, 0x80000000, v58
	v_cvt_pk_bf16_f32 v2, v2, v2
	ds_write_b16 v66, v2 offset:40256
	v_xor_b32_e32 v2, 0x80000000, v59
	v_cvt_pk_bf16_f32 v2, v2, v2
	ds_write_b16 v66, v2 offset:40528
	v_xor_b32_e32 v2, 0x80000000, v60
	v_cvt_pk_bf16_f32 v2, v2, v2
	ds_write_b16 v66, v2 offset:40800
	v_xor_b32_e32 v2, 0x80000000, v61
	v_cvt_pk_bf16_f32 v2, v2, v2
	ds_write_b16 v66, v2 offset:41072
	v_xor_b32_e32 v2, 0x80000000, v62
	v_cvt_pk_bf16_f32 v2, v2, v2
	ds_write_b16 v66, v2 offset:42432
	v_xor_b32_e32 v2, 0x80000000, v63
	v_cvt_pk_bf16_f32 v2, v2, v2
	ds_write_b16 v66, v2 offset:42704
	v_xor_b32_e32 v2, 0x80000000, v64
	v_cvt_pk_bf16_f32 v2, v2, v2
	ds_write_b16 v66, v2 offset:42976
	v_xor_b32_e32 v2, 0x80000000, v65
	v_cvt_pk_bf16_f32 v2, v2, v2
	ds_write_b16 v66, v2 offset:43248
	v_xor_b32_e32 v2, 0x80000000, v34
	v_cvt_pk_bf16_f32 v2, v2, v2
	ds_write_b16 v66, v2 offset:44608
	v_xor_b32_e32 v2, 0x80000000, v35
	v_cvt_pk_bf16_f32 v2, v2, v2
	ds_write_b16 v66, v2 offset:44880
	v_xor_b32_e32 v2, 0x80000000, v36
	v_cvt_pk_bf16_f32 v2, v2, v2
	ds_write_b16 v66, v2 offset:45152
	v_xor_b32_e32 v2, 0x80000000, v37
	v_cvt_pk_bf16_f32 v2, v2, v2
	ds_write_b16 v66, v2 offset:45424
	v_xor_b32_e32 v2, 0x80000000, v38
	v_cvt_pk_bf16_f32 v2, v2, v2
	ds_write_b16 v66, v2 offset:46784
	v_xor_b32_e32 v2, 0x80000000, v39
	v_cvt_pk_bf16_f32 v2, v2, v2
	ds_write_b16 v66, v2 offset:47056
	v_xor_b32_e32 v2, 0x80000000, v40
	v_cvt_pk_bf16_f32 v2, v2, v2
	ds_write_b16 v66, v2 offset:47328
	v_xor_b32_e32 v2, 0x80000000, v41
	v_cvt_pk_bf16_f32 v2, v2, v2
	ds_write_b16 v66, v2 offset:47600
	v_xor_b32_e32 v2, 0x80000000, v42
	v_cvt_pk_bf16_f32 v2, v2, v2
	ds_write_b16 v66, v2 offset:48960
	v_xor_b32_e32 v2, 0x80000000, v43
	v_cvt_pk_bf16_f32 v2, v2, v2
	ds_write_b16 v66, v2 offset:49232
	v_xor_b32_e32 v2, 0x80000000, v44
	v_cvt_pk_bf16_f32 v2, v2, v2
	ds_write_b16 v66, v2 offset:49504
	v_xor_b32_e32 v2, 0x80000000, v45
	v_cvt_pk_bf16_f32 v2, v2, v2
	ds_write_b16 v66, v2 offset:49776
	v_xor_b32_e32 v2, 0x80000000, v46
	v_cvt_pk_bf16_f32 v2, v2, v2
	ds_write_b16 v66, v2 offset:51136
	v_xor_b32_e32 v2, 0x80000000, v47
	v_cvt_pk_bf16_f32 v2, v2, v2
	ds_write_b16 v66, v2 offset:51408
	v_xor_b32_e32 v2, 0x80000000, v48
	v_cvt_pk_bf16_f32 v2, v2, v2
	ds_write_b16 v66, v2 offset:51680
	v_xor_b32_e32 v2, 0x80000000, v49
	v_cvt_pk_bf16_f32 v2, v2, v2
	ds_write_b16 v66, v2 offset:51952
	s_branch .LBB0_313
